# grid barrier: XCD leaders add to TOP and every workgroup polls TOP directly (TOPGEN/XGEN hops removed)
# speedup vs baseline: 1.0101x; 1.0086x over previous
; __device__ __forceinline__ unsigned xb_ld(unsigned* p)              { return __hip_atomic_load(p, __ATOMIC_RELAXED, __HIP_MEMORY_SCOPE_AGENT); }
; __device__ __forceinline__ unsigned xb_add(unsigned* p, unsigned v) { return __hip_atomic_fetch_add(p, v, __ATOMIC_RELAXED, __HIP_MEMORY_SCOPE_AGENT); }
; #define XB_SPIN(cond, bar) do { unsigned _sp = 0; while (cond) { __builtin_amdgcn_s_sleep(1); \
;     if ((++_sp & 255u) == 0u) { if (xb_ld(&(bar)[XB_TMO])) break; if (_sp > XB_SPIN_CAP) { atomicAdd(&(bar)[XB_TMO], 1u); break; } } } } while (0)
; __device__ __forceinline__ void xcd_barrier(const XcdBarrier& b) {
;     asm volatile("s_waitcnt vmcnt(0)" ::: "memory");
;     __syncthreads();
;     if (threadIdx.x == 0) {
;         unsigned* bar = b.bar;
;         __builtin_amdgcn_s_waitcnt(0);
;         unsigned nloc = b.st[0], nx = b.st[1];
;         if (nloc == 0u) { xcd_barrier_complete(bar, b.x, nloc, nx); b.st[0] = nloc; b.st[1] = nx; }
;         const unsigned old = xb_add(&bar[XB_XSUB(b.x)], 1u);
;         const unsigned gen = old / nloc;
;         if (old + 1u == (gen + 1u) * nloc) {
;             __builtin_amdgcn_fence(__ATOMIC_RELEASE, "agent");
;             asm volatile("s_waitcnt vmcnt(0)" ::: "memory");
;             const unsigned og = xb_add(&bar[XB_TOP], 1u);
;             const unsigned tg = og / nx;
;             if (og + 1u == (tg + 1u) * nx) xb_add(&bar[XB_TOPGEN], 1u);
;             else XB_SPIN(xb_ld(&bar[XB_TOPGEN]) == tg, bar);
;             __builtin_amdgcn_fence(__ATOMIC_ACQUIRE, "agent");
;             xb_add(&bar[XB_XGEN(b.x)], 1u);
;             asm volatile("s_waitcnt vmcnt(0)" ::: "memory");
;         } else {
;             XB_SPIN(xb_ld(&bar[XB_XGEN(b.x)]) == gen, bar);
;             __builtin_amdgcn_fence(__ATOMIC_ACQUIRE, "agent");
;             asm volatile("s_waitcnt vmcnt(0)" ::: "memory");
;         }
;     }
;     __syncthreads();
.LBB0_590:
	v_readlane_b32 s2, v254, 0
	v_readlane_b32 s3, v254, 1
	v_mov_b32_e32 v1, 1
	v_sub_u32_e32 v4, 0, v2
	s_nop 2
	global_atomic_add v3, v96, v1, s[2:3] sc0
	v_cvt_f32_u32_e32 v1, v2
	v_rcp_iflag_f32_e32 v1, v1
	s_nop 0
	v_mul_f32_e32 v1, 0x4f7ffffe, v1
	v_cvt_u32_f32_e32 v1, v1
	v_mul_lo_u32 v4, v4, v1
	v_mul_hi_u32 v4, v1, v4
	v_add_u32_e32 v1, v1, v4
	s_waitcnt vmcnt(0)
	v_mul_hi_u32 v1, v3, v1
	v_mul_lo_u32 v4, v1, v2
	v_sub_u32_e32 v4, v3, v4
	v_add_u32_e32 v5, 1, v1
	v_cmp_ge_u32_e32 vcc, v4, v2
	v_add_u32_e32 v3, 1, v3
	s_nop 0
	v_cndmask_b32_e32 v1, v1, v5, vcc
	v_sub_u32_e32 v5, v4, v2
	v_cndmask_b32_e32 v4, v4, v5, vcc
	v_add_u32_e32 v5, 1, v1
	v_cmp_ge_u32_e32 vcc, v4, v2
	s_nop 1
	v_cndmask_b32_e32 v1, v1, v5, vcc
	v_mul_lo_u32 v4, v2, v1
	v_add_u32_e32 v2, v4, v2
	v_cmp_ne_u32_e32 vcc, v3, v2
	v_add_u32_e32 v4, 1, v1
	s_waitcnt lgkmcnt(0)
	v_mul_lo_u32 v4, v4, v0
	v_readlane_b32 s2, v254, 4
	v_readlane_b32 s3, v254, 5
	s_nop 4
	s_cbranch_vccnz .Lxb_poll
	buffer_wbl2 sc1
	s_waitcnt vmcnt(0)
	v_mov_b32_e32 v1, 1
	global_atomic_add v96, v1, s[2:3]
.Lxb_poll:
	s_mov_b32 s6, 0
.Lxb_spin:
	global_load_dword v1, v96, s[2:3] sc1
	s_waitcnt vmcnt(0)
	v_cmp_ge_u32_e32 vcc, v1, v4
	s_cbranch_vccnz .Lxb_done
	s_sleep 1
	s_add_i32 s6, s6, 1
	s_cmp_lt_u32 s6, 0x40000
	s_cbranch_scc1 .Lxb_spin
.Lxb_done:
	buffer_inv sc1
	s_waitcnt vmcnt(0)
